# GDN prep: the four gate-parameter loads of the single-wave gate/cumsum part issued at item start (hidden behind the conv section)
# speedup vs baseline: 1.0116x; 1.0016x over previous
.LBB0_760:
	s_lshr_b32 s2, s13, 2
	s_and_b32 s37, s13, 3
	v_mov_b32_e32 v106, v228
	s_bfe_u32 s8, s13, 0x60002
	s_lshl_b32 s5, s2, 6
	s_lshl_b32 s4, s37, 7
	s_cmp_lg_u32 s8, 0
	v_ashrrev_i32_e32 v104, 3, v106
	s_cselect_b64 s[8:9], -1, 0
	v_cmp_lt_i32_e32 vcc, 2, v104
	s_waitcnt vmcnt(0)
	v_add_u32_e32 v0, -3, v104
	s_or_b64 vcc, s[8:9], vcc
	v_cndmask_b32_e32 v0, 0, v0, vcc
	v_cndmask_b32_e64 v44, 0, 1.0, vcc
	v_cmp_lt_i32_e32 vcc, 1, v104
	v_add_u32_e32 v4, -2, v104
	s_or_b64 vcc, s[8:9], vcc
	v_cndmask_b32_e32 v4, 0, v4, vcc
	v_cndmask_b32_e64 v42, 0, 1.0, vcc
	v_cmp_lt_i32_e32 vcc, 0, v104
	v_add_u32_e32 v8, -1, v104
	s_or_b64 vcc, s[8:9], vcc
	v_cndmask_b32_e32 v8, 0, v8, vcc
	v_cndmask_b32_e64 v40, 0, 1.0, vcc
	v_cmp_lt_i32_e32 vcc, -1, v104
	s_movk_i32 s2, 0x110
	s_or_b64 vcc, s[8:9], vcc
	v_and_b32_e32 v105, 7, v106
	v_mul_lo_u32 v109, v104, s2
	s_movk_i32 s2, 0x410
	v_cndmask_b32_e32 v14, 0, v104, vcc
	v_lshlrev_b32_e32 v108, 4, v105
	v_mul_lo_u32 v1, v104, s2
	v_add_u32_e32 v0, s5, v0
	v_mov_b64_e32 v[12:13], s[94:95]
	v_add_u32_e32 v4, s5, v4
	v_add_u32_e32 v8, s5, v8
	v_add_u32_e32 v14, s5, v14
	v_add_u32_e32 v107, 0, v1
	v_or_b32_e32 v39, s4, v108
	v_mad_i64_i32 v[0:1], s[38:39], v0, s66, v[12:13]
	v_mad_i64_i32 v[4:5], s[38:39], v4, s66, v[12:13]
	v_mad_i64_i32 v[8:9], s[38:39], v8, s66, v[12:13]
	v_mad_i64_i32 v[12:13], s[8:9], v14, s66, v[12:13]
	v_lshl_add_u64 v[46:47], v[0:1], 0, s[26:27]
	v_lshlrev_b32_e32 v16, 1, v39
	v_lshl_add_u64 v[48:49], v[4:5], 0, s[26:27]
	v_lshl_add_u64 v[50:51], v[8:9], 0, s[26:27]
	v_lshl_add_u64 v[52:53], v[12:13], 0, s[26:27]
	v_lshl_add_u64 v[0:1], v[46:47], 0, v[16:17]
	v_lshl_add_u64 v[4:5], v[48:49], 0, v[16:17]
	v_lshl_add_u64 v[8:9], v[50:51], 0, v[16:17]
	v_lshl_add_u64 v[12:13], v[52:53], 0, v[16:17]
	global_load_dwordx4 v[30:33], v[0:1], off
	s_nop 0
	global_load_dwordx4 v[0:3], v[0:1], off offset:16
	s_nop 0
	global_load_dwordx4 v[26:29], v[4:5], off
	s_nop 0
	global_load_dwordx4 v[4:7], v[4:5], off offset:16
	s_nop 0
	global_load_dwordx4 v[22:25], v[8:9], off
	s_nop 0
	global_load_dwordx4 v[8:11], v[8:9], off offset:16
	s_nop 0
	global_load_dwordx4 v[18:21], v[12:13], off
	s_nop 0
	global_load_dwordx4 v[12:15], v[12:13], off offset:16
	s_mov_b32 s8, 0
	s_ashr_i32 s9, s8, 31
	s_lshl_b64 s[8:9], s[8:9], 3
	s_add_u32 s8, s0, s8
	s_addc_u32 s9, s1, s9
	s_load_dwordx2 s[98:99], s[0:1], 0x98
	s_load_dwordx2 s[100:101], s[0:1], 0xa0
	s_load_dwordx2 s[8:9], s[8:9], 0x90
	v_lshlrev_b32_e32 v41, 2, v39
	v_cndmask_b32_e64 v38, 0, 1.0, vcc
	v_and_b32_e32 v111, 64, v234
	v_or_b32_e32 v16, 0x400, v16
	s_waitcnt lgkmcnt(0)
	v_or_b32_e32 v188, s5, v228
	v_lshlrev_b32_e32 v188, 5, v188
	v_lshl_add_u32 v188, s37, 2, v188
	global_load_dword v189, v188, s[42:43] offset:16
	global_load_dword v190, v188, s[42:43]
	v_mov_b32_e32 v188, s37
	v_or_b32_e32 v188, s35, v188
	v_lshlrev_b32_e32 v188, 2, v188
	global_load_dword v191, v188, s[98:99]
	global_load_dword v192, v188, s[100:101]
	s_add_u32 s98, s8, s16
	s_addc_u32 s99, s9, s17
	s_add_u32 s100, s8, s18
	s_addc_u32 s101, s9, s19
	s_add_u32 s30, s8, s22
	s_addc_u32 s31, s9, s23
	s_add_u32 s8, s8, s15
	s_addc_u32 s9, s9, s14
	global_load_dwordx4 v[34:37], v41, s[8:9] offset:48
	global_load_dwordx4 v[54:57], v41, s[8:9] offset:32
	global_load_dwordx4 v[58:61], v41, s[8:9] offset:16
	global_load_dwordx4 v[62:65], v41, s[8:9]
	global_load_dwordx4 v[140:143], v41, s[98:99] offset:48
	global_load_dwordx4 v[144:147], v41, s[98:99] offset:32
	global_load_dwordx4 v[148:151], v41, s[98:99] offset:16
	global_load_dwordx4 v[152:155], v41, s[98:99]
	global_load_dwordx4 v[156:159], v41, s[100:101] offset:48
	global_load_dwordx4 v[160:163], v41, s[100:101] offset:32
	global_load_dwordx4 v[164:167], v41, s[100:101] offset:16
	global_load_dwordx4 v[168:171], v41, s[100:101]
	global_load_dwordx4 v[172:175], v41, s[30:31] offset:48
	global_load_dwordx4 v[176:179], v41, s[30:31] offset:32
	global_load_dwordx4 v[180:183], v41, s[30:31] offset:16
	global_load_dwordx4 v[184:187], v41, s[30:31]
	s_mov_b32 s8, 0
	s_ashr_i32 s9, s8, 31
	s_lshl_b64 s[8:9], s[8:9], 3
	s_add_u32 s8, s0, s8
	s_addc_u32 s9, s1, s9
	s_load_dwordx2 s[8:9], s[8:9], 0x90
	v_lshl_add_u32 v110, v105, 6, v107
	s_waitcnt lgkmcnt(0)
	s_add_u32 s8, s8, s16
	s_addc_u32 s9, s9, s17
	s_waitcnt vmcnt(0)
	v_lshlrev_b32_e32 v43, 16, v30
	v_and_b32_e32 v30, 0xffff0000, v30
	v_lshlrev_b32_e32 v84, 16, v18
	v_and_b32_e32 v18, 0xffff0000, v18
	v_pk_mul_f32 v[58:59], v[44:45], v[58:59] op_sel_hi:[0,1]
	v_pk_mul_f32 v[62:63], v[44:45], v[62:63] op_sel_hi:[0,1]
	v_pk_mul_f32 v[64:65], v[44:45], v[64:65] op_sel_hi:[0,1]
	v_fma_f32 v82, v63, v30, 0
	v_lshlrev_b32_e32 v30, 16, v31
	v_fma_f32 v83, v62, v43, 0
	v_fma_f32 v81, v64, v30, 0
	v_and_b32_e32 v30, 0xffff0000, v31
	v_lshlrev_b32_e32 v43, 16, v32
	v_and_b32_e32 v32, 0xffff0000, v32
	v_fma_f32 v80, v65, v30, 0
	v_pk_mul_f32 v[30:31], v[44:45], v[60:61] op_sel_hi:[0,1]
	v_fma_f32 v78, v59, v32, 0
	v_lshlrev_b32_e32 v32, 16, v33
	v_fma_f32 v45, v30, v32, 0
	v_and_b32_e32 v30, 0xffff0000, v33
	v_fma_f32 v79, v58, v43, 0
	v_fma_f32 v43, v31, v30, 0
	v_pk_mul_f32 v[58:59], v[44:45], v[56:57] op_sel_hi:[0,1]
	v_pk_mul_f32 v[62:63], v[44:45], v[54:55] op_sel_hi:[0,1]
	v_pk_mul_f32 v[54:55], v[44:45], v[36:37] op_sel_hi:[0,1]
	v_pk_mul_f32 v[56:57], v[44:45], v[34:35] op_sel_hi:[0,1]
	v_mov_b64_e32 v[30:31], v[140:141]
	v_mov_b64_e32 v[32:33], v[142:143]
	v_mov_b64_e32 v[34:35], v[144:145]
	v_mov_b64_e32 v[36:37], v[146:147]
	v_mov_b64_e32 v[64:65], v[148:149]
	v_mov_b64_e32 v[66:67], v[150:151]
	v_mov_b64_e32 v[68:69], v[152:153]
	v_mov_b64_e32 v[70:71], v[154:155]
	s_mov_b32 s8, 0
	s_ashr_i32 s9, s8, 31
	s_lshl_b64 s[8:9], s[8:9], 3
	s_add_u32 s8, s0, s8
	s_addc_u32 s9, s1, s9
	s_load_dwordx2 s[8:9], s[8:9], 0x90
	s_waitcnt lgkmcnt(0)
	s_add_u32 s8, s8, s18
	s_addc_u32 s9, s9, s19
	s_waitcnt vmcnt(0)
	v_pk_mul_f32 v[60:61], v[42:43], v[70:71] op_sel_hi:[0,1]
	v_pk_mul_f32 v[68:69], v[42:43], v[68:69] op_sel_hi:[0,1]
	v_lshlrev_b32_e32 v70, 16, v26
	v_and_b32_e32 v26, 0xffff0000, v26
	v_fmac_f32_e32 v82, v69, v26
	v_lshlrev_b32_e32 v26, 16, v27
	v_fmac_f32_e32 v81, v60, v26
	v_and_b32_e32 v26, 0xffff0000, v27
	v_fmac_f32_e32 v80, v61, v26
	v_pk_mul_f32 v[60:61], v[42:43], v[64:65] op_sel_hi:[0,1]
	v_lshlrev_b32_e32 v64, 16, v28
	v_and_b32_e32 v28, 0xffff0000, v28
	v_pk_mul_f32 v[26:27], v[42:43], v[66:67] op_sel_hi:[0,1]
	v_fmac_f32_e32 v78, v61, v28
	v_lshlrev_b32_e32 v28, 16, v29
	v_fmac_f32_e32 v45, v26, v28
	v_and_b32_e32 v26, 0xffff0000, v29
	v_fmac_f32_e32 v43, v27, v26
	v_fmac_f32_e32 v83, v68, v70
	v_fmac_f32_e32 v79, v60, v64
	v_pk_mul_f32 v[66:67], v[42:43], v[36:37] op_sel_hi:[0,1]
	v_pk_mul_f32 v[70:71], v[42:43], v[34:35] op_sel_hi:[0,1]
	v_pk_mul_f32 v[60:61], v[42:43], v[32:33] op_sel_hi:[0,1]
	v_pk_mul_f32 v[64:65], v[42:43], v[30:31] op_sel_hi:[0,1]
	v_mov_b64_e32 v[26:27], v[156:157]
	v_mov_b64_e32 v[28:29], v[158:159]
	v_mov_b64_e32 v[30:31], v[160:161]
	v_mov_b64_e32 v[32:33], v[162:163]
	v_mov_b64_e32 v[34:35], v[164:165]
	v_mov_b64_e32 v[36:37], v[166:167]
	v_mov_b64_e32 v[72:73], v[168:169]
	v_mov_b64_e32 v[74:75], v[170:171]
	s_mov_b32 s8, 0
	s_ashr_i32 s9, s8, 31
	s_lshl_b64 s[8:9], s[8:9], 3
	s_add_u32 s8, s0, s8
	s_addc_u32 s9, s1, s9
	s_load_dwordx2 s[8:9], s[8:9], 0x90
	s_waitcnt lgkmcnt(0)
	s_add_u32 s8, s8, s22
	s_addc_u32 s9, s9, s23
	s_waitcnt vmcnt(2)
	v_pk_mul_f32 v[76:77], v[40:41], v[30:31] op_sel_hi:[0,1]
	s_waitcnt vmcnt(1)
	v_pk_mul_f32 v[34:35], v[40:41], v[34:35] op_sel_hi:[0,1]
	s_waitcnt vmcnt(0)
	v_pk_mul_f32 v[68:69], v[40:41], v[74:75] op_sel_hi:[0,1]
	v_pk_mul_f32 v[72:73], v[40:41], v[72:73] op_sel_hi:[0,1]
	v_lshlrev_b32_e32 v74, 16, v22
	v_and_b32_e32 v22, 0xffff0000, v22
	v_fmac_f32_e32 v82, v73, v22
	v_lshlrev_b32_e32 v22, 16, v23
	v_fmac_f32_e32 v81, v68, v22
	v_and_b32_e32 v22, 0xffff0000, v23
	v_fmac_f32_e32 v80, v69, v22
	v_pk_mul_f32 v[22:23], v[40:41], v[36:37] op_sel_hi:[0,1]
	v_lshlrev_b32_e32 v36, 16, v24
	v_and_b32_e32 v24, 0xffff0000, v24
	v_fmac_f32_e32 v78, v35, v24
	v_lshlrev_b32_e32 v24, 16, v25
	v_fmac_f32_e32 v45, v22, v24
	v_and_b32_e32 v22, 0xffff0000, v25
	v_fmac_f32_e32 v83, v72, v74
	v_fmac_f32_e32 v79, v34, v36
	v_fmac_f32_e32 v43, v23, v22
	v_pk_mul_f32 v[74:75], v[40:41], v[32:33] op_sel_hi:[0,1]
	v_pk_mul_f32 v[68:69], v[40:41], v[28:29] op_sel_hi:[0,1]
	v_pk_mul_f32 v[72:73], v[40:41], v[26:27] op_sel_hi:[0,1]
	v_mov_b64_e32 v[22:23], v[172:173]
	v_mov_b64_e32 v[24:25], v[174:175]
	v_mov_b64_e32 v[26:27], v[176:177]
	v_mov_b64_e32 v[28:29], v[178:179]
	v_mov_b64_e32 v[30:31], v[180:181]
	v_mov_b64_e32 v[32:33], v[182:183]
	v_mov_b64_e32 v[34:35], v[184:185]
	v_mov_b64_e32 v[36:37], v[186:187]
	s_waitcnt vmcnt(2)
	v_pk_mul_f32 v[26:27], v[38:39], v[26:27] op_sel_hi:[0,1]
	s_waitcnt vmcnt(1)
	v_pk_mul_f32 v[30:31], v[38:39], v[30:31] op_sel_hi:[0,1]
	s_waitcnt vmcnt(0)
	v_pk_mul_f32 v[34:35], v[38:39], v[34:35] op_sel_hi:[0,1]
	v_pk_mul_f32 v[36:37], v[38:39], v[36:37] op_sel_hi:[0,1]
	v_fmac_f32_e32 v82, v35, v18
	v_lshlrev_b32_e32 v18, 16, v19
	v_fmac_f32_e32 v81, v36, v18
	v_and_b32_e32 v18, 0xffff0000, v19
	v_fmac_f32_e32 v80, v37, v18
	v_pk_mul_f32 v[18:19], v[38:39], v[32:33] op_sel_hi:[0,1]
	v_lshlrev_b32_e32 v32, 16, v20
	v_and_b32_e32 v20, 0xffff0000, v20
	v_fmac_f32_e32 v83, v34, v84
	v_fmac_f32_e32 v78, v31, v20
	v_lshlrev_b32_e32 v20, 16, v21
	v_fmac_f32_e32 v45, v18, v20
	v_and_b32_e32 v18, 0xffff0000, v21
	v_pk_mul_f32 v[20:21], v[38:39], v[22:23] op_sel_hi:[0,1]
	v_mul_f32_e32 v22, 0xbfb8aa3b, v83
	v_exp_f32_e32 v22, v22
	v_fmac_f32_e32 v79, v30, v32
	v_fmac_f32_e32 v43, v19, v18
	v_and_b32_e32 v23, 0xffff0000, v0
	v_add_f32_e32 v22, 1.0, v22
	v_rcp_f32_e32 v22, v22
	v_pk_mul_f32 v[18:19], v[38:39], v[24:25] op_sel_hi:[0,1]
	v_and_b32_e32 v25, 0xffff0000, v4
	v_lshlrev_b32_e32 v24, 16, v4
	v_mul_f32_e32 v30, v83, v22
	v_mul_f32_e32 v22, 0xbfb8aa3b, v82
	v_exp_f32_e32 v22, v22
	v_lshlrev_b32_e32 v4, 16, v9
	v_pk_mul_f32 v[28:29], v[38:39], v[28:29] op_sel_hi:[0,1]
	v_add_f32_e32 v22, 1.0, v22
	v_rcp_f32_e32 v22, v22
	s_nop 0
	v_mul_f32_e32 v31, v82, v22
	v_mul_f32_e32 v22, 0xbfb8aa3b, v81
	v_exp_f32_e32 v22, v22
	s_nop 0
	v_add_f32_e32 v22, 1.0, v22
	v_rcp_f32_e32 v22, v22
	s_nop 0
	v_mul_f32_e32 v32, v81, v22
	v_mul_f32_e32 v22, 0xbfb8aa3b, v80
	v_exp_f32_e32 v22, v22
	s_nop 0
	v_add_f32_e32 v22, 1.0, v22
	v_rcp_f32_e32 v22, v22
	s_nop 0
	v_mul_f32_e32 v33, v80, v22
	v_mul_f32_e32 v22, 0xbfb8aa3b, v79
	v_exp_f32_e32 v22, v22
	s_nop 0
	v_add_f32_e32 v22, 1.0, v22
	v_rcp_f32_e32 v22, v22
	s_nop 0
	v_mul_f32_e32 v34, v79, v22
	v_mul_f32_e32 v22, 0xbfb8aa3b, v78
	v_exp_f32_e32 v22, v22
	s_nop 0
	v_add_f32_e32 v22, 1.0, v22
	v_rcp_f32_e32 v22, v22
	s_nop 0
	v_mul_f32_e32 v35, v78, v22
	v_mul_f32_e32 v22, 0xbfb8aa3b, v45
	v_exp_f32_e32 v22, v22
	s_nop 0
	v_add_f32_e32 v22, 1.0, v22
	v_rcp_f32_e32 v22, v22
	s_nop 0
	v_mul_f32_e32 v36, v45, v22
	v_mul_f32_e32 v22, 0xbfb8aa3b, v43
	v_exp_f32_e32 v22, v22
	s_nop 0
	v_add_f32_e32 v22, 1.0, v22
	v_rcp_f32_e32 v22, v22
	s_nop 0
	v_mul_f32_e32 v37, v43, v22
	v_lshlrev_b32_e32 v22, 16, v0
	v_pk_fma_f32 v[22:23], v[62:63], v[22:23], 0 op_sel_hi:[1,1,0]
	v_mul_f32_e32 v43, v31, v31
	v_pk_fma_f32 v[22:23], v[70:71], v[24:25], v[22:23]
	v_and_b32_e32 v25, 0xffff0000, v8
	v_lshlrev_b32_e32 v24, 16, v8
	v_pk_fma_f32 v[22:23], v[76:77], v[24:25], v[22:23]
	v_and_b32_e32 v25, 0xffff0000, v12
	v_lshlrev_b32_e32 v24, 16, v12
	v_pk_fma_f32 v[22:23], v[26:27], v[24:25], v[22:23]
	v_fmac_f32_e32 v43, v30, v30
	v_mul_f32_e32 v0, 0xbfb8aa3b, v22
	v_exp_f32_e32 v0, v0
	v_fmac_f32_e32 v43, v32, v32
	v_fmac_f32_e32 v43, v33, v33
	v_fmac_f32_e32 v43, v34, v34
	v_add_f32_e32 v0, 1.0, v0
	v_rcp_f32_e32 v24, v0
	v_mul_f32_e32 v0, 0xbfb8aa3b, v23
	v_exp_f32_e32 v0, v0
	v_fmac_f32_e32 v43, v35, v35
	v_fmac_f32_e32 v43, v36, v36
	v_fmac_f32_e32 v43, v37, v37
	v_add_f32_e32 v0, 1.0, v0
	v_rcp_f32_e32 v25, v0
	s_nop 0
	v_pk_mul_f32 v[22:23], v[22:23], v[24:25]
	s_nop 0
	v_pk_mul_f32 v[24:25], v[22:23], v[22:23]
	s_nop 0
	v_add_f32_e32 v0, v24, v43
	v_add_f32_e32 v8, v25, v0
	v_and_b32_e32 v25, 0xffff0000, v1
	v_lshlrev_b32_e32 v24, 16, v1
	v_pk_fma_f32 v[0:1], v[58:59], v[24:25], 0 op_sel_hi:[1,1,0]
	v_and_b32_e32 v25, 0xffff0000, v5
	v_lshlrev_b32_e32 v24, 16, v5
	v_pk_fma_f32 v[0:1], v[66:67], v[24:25], v[0:1]
	v_and_b32_e32 v5, 0xffff0000, v9
	v_pk_fma_f32 v[0:1], v[74:75], v[4:5], v[0:1]
	v_and_b32_e32 v5, 0xffff0000, v13
	v_lshlrev_b32_e32 v4, 16, v13
	v_pk_fma_f32 v[0:1], v[28:29], v[4:5], v[0:1]
	v_and_b32_e32 v9, 0xffff0000, v6
	v_mul_f32_e32 v4, 0xbfb8aa3b, v0
	v_mul_f32_e32 v5, 0xbfb8aa3b, v1
	v_exp_f32_e32 v4, v4
	v_exp_f32_e32 v5, v5
	v_add_f32_e32 v4, 1.0, v4
	v_add_f32_e32 v5, 1.0, v5
	v_rcp_f32_e32 v4, v4
	v_rcp_f32_e32 v5, v5
	s_nop 0
	v_pk_mul_f32 v[0:1], v[0:1], v[4:5]
	s_nop 0
	v_pk_mul_f32 v[4:5], v[0:1], v[0:1]
	s_nop 0
	v_add_f32_e32 v4, v4, v8
	v_add_f32_e32 v12, v5, v4
	v_and_b32_e32 v5, 0xffff0000, v2
	v_lshlrev_b32_e32 v4, 16, v2
	v_pk_fma_f32 v[4:5], v[56:57], v[4:5], 0 op_sel_hi:[1,1,0]
	v_lshlrev_b32_e32 v8, 16, v6
	v_pk_fma_f32 v[4:5], v[64:65], v[8:9], v[4:5]
	v_and_b32_e32 v9, 0xffff0000, v10
	v_lshlrev_b32_e32 v8, 16, v10
	v_pk_fma_f32 v[4:5], v[72:73], v[8:9], v[4:5]
	v_and_b32_e32 v9, 0xffff0000, v14
	v_lshlrev_b32_e32 v8, 16, v14
	v_pk_fma_f32 v[4:5], v[20:21], v[8:9], v[4:5]
	v_lshlrev_b32_e32 v6, 16, v11
	v_mul_f32_e32 v2, 0xbfb8aa3b, v4
	v_exp_f32_e32 v2, v2
	s_nop 0
	v_add_f32_e32 v2, 1.0, v2
	v_rcp_f32_e32 v8, v2
	v_mul_f32_e32 v2, 0xbfb8aa3b, v5
	v_exp_f32_e32 v2, v2
	s_nop 0
	v_add_f32_e32 v2, 1.0, v2
	v_rcp_f32_e32 v9, v2
	s_nop 0
	v_pk_mul_f32 v[4:5], v[4:5], v[8:9]
	s_nop 0
	v_pk_mul_f32 v[8:9], v[4:5], v[4:5]
	s_nop 0
	v_add_f32_e32 v2, v8, v12
	v_add_f32_e32 v10, v9, v2
	v_and_b32_e32 v9, 0xffff0000, v3
	v_lshlrev_b32_e32 v8, 16, v3
	v_pk_fma_f32 v[2:3], v[54:55], v[8:9], 0 op_sel_hi:[1,1,0]
	v_and_b32_e32 v9, 0xffff0000, v7
	v_lshlrev_b32_e32 v8, 16, v7
	v_pk_fma_f32 v[2:3], v[60:61], v[8:9], v[2:3]
	v_and_b32_e32 v7, 0xffff0000, v11
	v_pk_fma_f32 v[2:3], v[68:69], v[6:7], v[2:3]
	v_and_b32_e32 v7, 0xffff0000, v15
	v_lshlrev_b32_e32 v6, 16, v15
	v_pk_fma_f32 v[2:3], v[18:19], v[6:7], v[2:3]
	v_add_u32_e32 v8, 64, v111
	v_mul_f32_e32 v6, 0xbfb8aa3b, v3
	v_exp_f32_e32 v6, v6
	s_nop 0
	v_add_f32_e32 v6, 1.0, v6
	v_rcp_f32_e32 v7, v6
	v_mul_f32_e32 v6, 0xbfb8aa3b, v2
	v_exp_f32_e32 v6, v6
	s_nop 0
	v_add_f32_e32 v6, 1.0, v6
	v_rcp_f32_e32 v6, v6
	s_nop 0
	v_pk_mul_f32 v[2:3], v[2:3], v[6:7]
	s_nop 0
	v_pk_mul_f32 v[6:7], v[2:3], v[2:3]
	s_nop 0
	v_add_f32_e32 v6, v6, v10
	v_add_f32_e32 v6, v7, v6
	v_xor_b32_e32 v7, 1, v234
	v_cmp_lt_i32_e32 vcc, v7, v8
	s_nop 1
	v_cndmask_b32_e32 v7, v234, v7, vcc
	v_lshlrev_b32_e32 v45, 2, v7
	ds_bpermute_b32 v7, v45, v6
	s_waitcnt lgkmcnt(0)
	v_add_f32_e32 v6, v6, v7
	v_xor_b32_e32 v7, 2, v234
	v_cmp_lt_i32_e32 vcc, v7, v8
	s_nop 1
	v_cndmask_b32_e32 v7, v234, v7, vcc
	v_lshlrev_b32_e32 v112, 2, v7
	ds_bpermute_b32 v7, v112, v6
	s_waitcnt lgkmcnt(0)
	v_add_f32_e32 v6, v6, v7
	v_xor_b32_e32 v7, 4, v234
	v_cmp_lt_i32_e32 vcc, v7, v8
	s_nop 1
	v_cndmask_b32_e32 v7, v234, v7, vcc
	v_lshlrev_b32_e32 v113, 2, v7
	ds_bpermute_b32 v7, v113, v6
	s_waitcnt lgkmcnt(0)
	v_add_f32_e32 v6, v6, v7
	v_add_f32_e32 v6, 0x358637bd, v6
	v_cmp_gt_f32_e32 vcc, s33, v6
	v_mul_f32_e32 v7, 0x4b800000, v6
	s_nop 0
	v_cndmask_b32_e32 v6, v6, v7, vcc
	v_rsq_f32_e32 v6, v6
	s_nop 0
	v_mul_f32_e32 v7, 0x45800000, v6
	v_cndmask_b32_e32 v6, v6, v7, vcc
	v_mul_f32_e32 v6, 0x3db504f3, v6
	v_mul_f32_e32 v7, v30, v6
	v_mul_f32_e32 v8, v31, v6
	v_mul_f32_e32 v9, v32, v6
	v_mul_f32_e32 v10, v33, v6
	v_mul_f32_e32 v11, v34, v6
	v_mul_f32_e32 v12, v35, v6
	v_mul_f32_e32 v13, v36, v6
	v_mul_f32_e32 v14, v37, v6
	v_mul_f32_e32 v15, v22, v6
	v_mul_f32_e32 v18, v23, v6
	v_mul_f32_e32 v0, v0, v6
	v_mul_f32_e32 v1, v1, v6
	v_mul_f32_e32 v4, v4, v6
	v_mul_f32_e32 v5, v5, v6
	v_mul_f32_e32 v2, v2, v6
	v_mul_f32_e32 v3, v3, v6
	v_lshlrev_b32_e32 v6, 5, v105
	v_add3_u32 v43, 0, v6, v109
	v_cvt_pk_bf16_f32 v6, v7, v8
	v_add_u32_e32 v8, 0x4400, v43
	v_cvt_pk_bf16_f32 v7, v9, v10
	ds_write2_b32 v8, v6, v7 offset1:1
	v_cvt_pk_bf16_f32 v6, v11, v12
	v_cvt_pk_bf16_f32 v0, v0, v1
	v_cvt_pk_bf16_f32 v7, v13, v14
	ds_write2_b32 v8, v6, v7 offset0:2 offset1:3
	v_cvt_pk_bf16_f32 v6, v15, v18
	ds_write2_b32 v8, v6, v0 offset0:4 offset1:5
	v_cvt_pk_bf16_f32 v0, v4, v5
	v_cvt_pk_bf16_f32 v1, v2, v3
	ds_write2_b32 v8, v0, v1 offset0:6 offset1:7
	v_lshl_add_u64 v[0:1], v[46:47], 0, v[16:17]
	global_load_dwordx4 v[30:33], v[0:1], off
	global_load_dwordx4 v[12:15], v[0:1], off offset:16
	v_lshl_add_u64 v[0:1], v[48:49], 0, v[16:17]
	global_load_dwordx4 v[26:29], v[0:1], off
	global_load_dwordx4 v[8:11], v[0:1], off offset:16
	v_lshl_add_u64 v[0:1], v[50:51], 0, v[16:17]
	global_load_dwordx4 v[22:25], v[0:1], off
	global_load_dwordx4 v[4:7], v[0:1], off offset:16
	v_lshl_add_u64 v[0:1], v[52:53], 0, v[16:17]
	global_load_dwordx4 v[18:21], v[0:1], off
	s_nop 0
	global_load_dwordx4 v[0:3], v[0:1], off offset:16
	s_mov_b32 s8, 0
	s_ashr_i32 s9, s8, 31
	s_lshl_b64 s[8:9], s[8:9], 3
	s_add_u32 s8, s0, s8
	s_addc_u32 s9, s1, s9
	s_load_dwordx2 s[8:9], s[8:9], 0x90
	s_waitcnt lgkmcnt(0)
	s_add_u32 s98, s8, s16
	s_addc_u32 s99, s9, s17
	s_add_u32 s100, s8, s18
	s_addc_u32 s101, s9, s19
	s_add_u32 s30, s8, s22
	s_addc_u32 s31, s9, s23
	s_add_u32 s8, s8, s15
	s_addc_u32 s9, s9, s14
	global_load_dwordx4 v[58:61], v41, s[8:9] offset:2096
	global_load_dwordx4 v[62:65], v41, s[8:9] offset:2080
	global_load_dwordx4 v[34:37], v41, s[8:9] offset:2064
	global_load_dwordx4 v[54:57], v41, s[8:9] offset:2048
	global_load_dwordx4 v[140:143], v41, s[98:99] offset:2096
	global_load_dwordx4 v[144:147], v41, s[98:99] offset:2080
	global_load_dwordx4 v[148:151], v41, s[98:99] offset:2064
	global_load_dwordx4 v[152:155], v41, s[98:99] offset:2048
	global_load_dwordx4 v[156:159], v41, s[100:101] offset:2096
	global_load_dwordx4 v[160:163], v41, s[100:101] offset:2080
	global_load_dwordx4 v[164:167], v41, s[100:101] offset:2064
	global_load_dwordx4 v[168:171], v41, s[100:101] offset:2048
	global_load_dwordx4 v[172:175], v41, s[30:31] offset:2096
	global_load_dwordx4 v[176:179], v41, s[30:31] offset:2080
	global_load_dwordx4 v[180:183], v41, s[30:31] offset:2064
	global_load_dwordx4 v[184:187], v41, s[30:31] offset:2048
	s_mov_b32 s8, 0
	s_ashr_i32 s9, s8, 31
	s_lshl_b64 s[8:9], s[8:9], 3
	s_add_u32 s8, s0, s8
	s_addc_u32 s9, s1, s9
	s_load_dwordx2 s[8:9], s[8:9], 0x90
	s_waitcnt lgkmcnt(0)
	s_add_u32 s8, s8, s16
	s_addc_u32 s9, s9, s17
	s_waitcnt vmcnt(0)
	v_pk_mul_f32 v[92:93], v[44:45], v[60:61] op_sel_hi:[0,1]
	v_pk_mul_f32 v[74:75], v[44:45], v[58:59] op_sel_hi:[0,1]
	v_pk_mul_f32 v[66:67], v[44:45], v[34:35] op_sel_hi:[0,1]
	v_pk_mul_f32 v[78:79], v[44:45], v[54:55] op_sel_hi:[0,1]
	v_pk_mul_f32 v[34:35], v[44:45], v[64:65] op_sel_hi:[0,1]
	v_pk_mul_f32 v[54:55], v[44:45], v[62:63] op_sel_hi:[0,1]
	v_mov_b64_e32 v[82:83], v[140:141]
	v_mov_b64_e32 v[84:85], v[142:143]
	v_mov_b64_e32 v[58:59], v[144:145]
	v_mov_b64_e32 v[60:61], v[146:147]
	v_mov_b64_e32 v[88:89], v[148:149]
	v_mov_b64_e32 v[90:91], v[150:151]
	v_mov_b64_e32 v[62:63], v[152:153]
	v_mov_b64_e32 v[64:65], v[154:155]
	s_mov_b32 s8, 0
	s_ashr_i32 s9, s8, 31
	s_lshl_b64 s[8:9], s[8:9], 3
	s_add_u32 s8, s0, s8
	s_addc_u32 s9, s1, s9
	s_load_dwordx2 s[8:9], s[8:9], 0x90
	v_pk_mul_f32 v[70:71], v[44:45], v[56:57] op_sel_hi:[0,1]
	v_pk_mul_f32 v[56:57], v[44:45], v[36:37] op_sel_hi:[0,1]
	s_waitcnt lgkmcnt(0)
	s_add_u32 s8, s8, s18
	s_addc_u32 s9, s9, s19
	v_mov_b64_e32 v[100:101], v[156:157]
	v_mov_b64_e32 v[102:103], v[158:159]
	v_mov_b64_e32 v[114:115], v[160:161]
	v_mov_b64_e32 v[116:117], v[162:163]
	v_mov_b64_e32 v[118:119], v[164:165]
	v_mov_b64_e32 v[120:121], v[166:167]
	v_mov_b64_e32 v[94:95], v[168:169]
	v_mov_b64_e32 v[96:97], v[170:171]
	s_mov_b32 s8, 0
	s_ashr_i32 s9, s8, 31
	s_lshl_b64 s[8:9], s[8:9], 3
	s_add_u32 s8, s0, s8
	s_addc_u32 s9, s1, s9
	s_load_dwordx2 s[8:9], s[8:9], 0x90
	s_waitcnt lgkmcnt(0)
	s_add_u32 s8, s8, s22
	s_addc_u32 s9, s9, s23
	s_waitcnt vmcnt(7)
	v_pk_mul_f32 v[98:99], v[42:43], v[84:85] op_sel_hi:[0,1]
	s_waitcnt vmcnt(6)
	v_pk_mul_f32 v[36:37], v[42:43], v[60:61] op_sel_hi:[0,1]
	v_pk_mul_f32 v[60:61], v[42:43], v[58:59] op_sel_hi:[0,1]
	s_waitcnt vmcnt(4)
	v_pk_mul_f32 v[80:81], v[42:43], v[64:65] op_sel_hi:[0,1]
	v_pk_mul_f32 v[84:85], v[42:43], v[82:83] op_sel_hi:[0,1]
	v_pk_mul_f32 v[86:87], v[42:43], v[62:63] op_sel_hi:[0,1]
	v_pk_mul_f32 v[62:63], v[42:43], v[90:91] op_sel_hi:[0,1]
	v_pk_mul_f32 v[72:73], v[42:43], v[88:89] op_sel_hi:[0,1]
	s_waitcnt vmcnt(3)
	v_pk_mul_f32 v[130:131], v[40:41], v[100:101] op_sel_hi:[0,1]
	s_waitcnt vmcnt(2)
	v_pk_mul_f32 v[58:59], v[40:41], v[116:117] op_sel_hi:[0,1]
	s_waitcnt vmcnt(1)
	v_pk_mul_f32 v[68:69], v[40:41], v[120:121] op_sel_hi:[0,1]
	v_pk_mul_f32 v[82:83], v[40:41], v[118:119] op_sel_hi:[0,1]
	v_pk_mul_f32 v[64:65], v[40:41], v[114:115] op_sel_hi:[0,1]
	v_mov_b64_e32 v[114:115], v[172:173]
	v_mov_b64_e32 v[116:117], v[174:175]
	v_mov_b64_e32 v[118:119], v[176:177]
	v_mov_b64_e32 v[120:121], v[178:179]
	v_mov_b64_e32 v[122:123], v[180:181]
	v_mov_b64_e32 v[124:125], v[182:183]
	v_mov_b64_e32 v[126:127], v[184:185]
	v_mov_b64_e32 v[128:129], v[186:187]
	v_pk_mul_f32 v[102:103], v[40:41], v[102:103] op_sel_hi:[0,1]
	s_waitcnt vmcnt(4)
	v_pk_mul_f32 v[88:89], v[40:41], v[96:97] op_sel_hi:[0,1]
	v_pk_mul_f32 v[96:97], v[40:41], v[94:95] op_sel_hi:[0,1]
	s_waitcnt vmcnt(3)
	v_pk_mul_f32 v[114:115], v[38:39], v[114:115] op_sel_hi:[0,1]
	s_waitcnt vmcnt(2)
	v_pk_mul_f32 v[90:91], v[38:39], v[118:119] op_sel_hi:[0,1]
	v_and_b32_e32 v119, 0xffff0000, v14
	v_lshlrev_b32_e32 v118, 16, v14
	v_pk_fma_f32 v[74:75], v[74:75], v[118:119], 0 op_sel_hi:[1,1,0]
	v_and_b32_e32 v119, 0xffff0000, v10
	v_lshlrev_b32_e32 v118, 16, v10
	v_pk_fma_f32 v[74:75], v[84:85], v[118:119], v[74:75]
	v_and_b32_e32 v85, 0xffff0000, v6
	v_lshlrev_b32_e32 v84, 16, v6
	v_pk_fma_f32 v[74:75], v[130:131], v[84:85], v[74:75]
	v_and_b32_e32 v85, 0xffff0000, v2
	v_lshlrev_b32_e32 v84, 16, v2
	v_pk_fma_f32 v[74:75], v[114:115], v[84:85], v[74:75]
	v_and_b32_e32 v115, 0xffff0000, v15
	v_mul_f32_e32 v2, 0xbfb8aa3b, v74
	v_exp_f32_e32 v2, v2
	v_lshlrev_b32_e32 v114, 16, v15
	v_pk_fma_f32 v[14:15], v[92:93], v[114:115], 0 op_sel_hi:[1,1,0]
	v_and_b32_e32 v93, 0xffff0000, v11
	v_add_f32_e32 v2, 1.0, v2
	v_rcp_f32_e32 v84, v2
	v_mul_f32_e32 v2, 0xbfb8aa3b, v75
	v_exp_f32_e32 v2, v2
	v_lshlrev_b32_e32 v92, 16, v11
	v_pk_fma_f32 v[10:11], v[98:99], v[92:93], v[14:15]
	v_and_b32_e32 v15, 0xffff0000, v7
	v_lshlrev_b32_e32 v14, 16, v7
	v_pk_mul_f32 v[116:117], v[38:39], v[116:117] op_sel_hi:[0,1]
	v_add_f32_e32 v2, 1.0, v2
	v_pk_fma_f32 v[6:7], v[102:103], v[14:15], v[10:11]
	v_and_b32_e32 v11, 0xffff0000, v3
	v_lshlrev_b32_e32 v10, 16, v3
	v_rcp_f32_e32 v85, v2
	v_pk_fma_f32 v[2:3], v[116:117], v[10:11], v[6:7]
	v_lshlrev_b32_e32 v10, 16, v30
	v_and_b32_e32 v11, 0xffff0000, v30
	v_lshlrev_b32_e32 v30, 16, v31
	v_and_b32_e32 v31, 0xffff0000, v31
	v_pk_fma_f32 v[10:11], v[78:79], v[10:11], 0 op_sel_hi:[1,1,0]
	v_lshlrev_b32_e32 v14, 16, v26
	v_and_b32_e32 v15, 0xffff0000, v26
	v_pk_fma_f32 v[30:31], v[70:71], v[30:31], 0 op_sel_hi:[1,1,0]
	v_lshlrev_b32_e32 v26, 16, v27
	v_and_b32_e32 v27, 0xffff0000, v27
	v_pk_fma_f32 v[10:11], v[86:87], v[14:15], v[10:11]
	v_lshlrev_b32_e32 v14, 16, v22
	v_and_b32_e32 v15, 0xffff0000, v22
	v_pk_fma_f32 v[26:27], v[80:81], v[26:27], v[30:31]
	v_lshlrev_b32_e32 v22, 16, v23
	v_and_b32_e32 v23, 0xffff0000, v23
	s_waitcnt vmcnt(0)
	v_pk_mul_f32 v[128:129], v[38:39], v[128:129] op_sel_hi:[0,1]
	v_pk_fma_f32 v[10:11], v[96:97], v[14:15], v[10:11]
	v_lshlrev_b32_e32 v14, 16, v18
	v_and_b32_e32 v15, 0xffff0000, v18
	v_pk_fma_f32 v[22:23], v[88:89], v[22:23], v[26:27]
	v_lshlrev_b32_e32 v18, 16, v19
	v_and_b32_e32 v19, 0xffff0000, v19
	v_pk_fma_f32 v[18:19], v[128:129], v[18:19], v[22:23]
	v_lshlrev_b32_e32 v26, 16, v32
	v_mul_f32_e32 v16, 0xbfb8aa3b, v18
	v_exp_f32_e32 v16, v16
	v_and_b32_e32 v27, 0xffff0000, v32
	v_pk_fma_f32 v[26:27], v[66:67], v[26:27], 0 op_sel_hi:[1,1,0]
	v_lshlrev_b32_e32 v30, 16, v28
	v_add_f32_e32 v16, 1.0, v16
	v_rcp_f32_e32 v22, v16
	v_mul_f32_e32 v16, 0xbfb8aa3b, v19
	v_exp_f32_e32 v16, v16
	v_and_b32_e32 v31, 0xffff0000, v28
	v_pk_fma_f32 v[26:27], v[72:73], v[30:31], v[26:27]
	v_lshlrev_b32_e32 v30, 16, v24
	v_and_b32_e32 v31, 0xffff0000, v24
	v_pk_mul_f32 v[100:101], v[38:39], v[122:123] op_sel_hi:[0,1]
	v_pk_fma_f32 v[26:27], v[82:83], v[30:31], v[26:27]
	v_lshlrev_b32_e32 v30, 16, v20
	v_and_b32_e32 v31, 0xffff0000, v20
	v_add_f32_e32 v16, 1.0, v16
	v_pk_fma_f32 v[26:27], v[100:101], v[30:31], v[26:27]
	v_rcp_f32_e32 v23, v16
	v_mul_f32_e32 v16, 0xbfb8aa3b, v26
	v_lshlrev_b32_e32 v32, 16, v33
	v_and_b32_e32 v33, 0xffff0000, v33
	v_exp_f32_e32 v16, v16
	v_pk_fma_f32 v[32:33], v[56:57], v[32:33], 0 op_sel_hi:[1,1,0]
	v_lshlrev_b32_e32 v28, 16, v29
	v_and_b32_e32 v29, 0xffff0000, v29
	v_pk_fma_f32 v[28:29], v[62:63], v[28:29], v[32:33]
	v_lshlrev_b32_e32 v24, 16, v25
	v_and_b32_e32 v25, 0xffff0000, v25
	v_pk_fma_f32 v[24:25], v[68:69], v[24:25], v[28:29]
	v_lshlrev_b32_e32 v28, 16, v12
	v_and_b32_e32 v29, 0xffff0000, v12
	v_pk_fma_f32 v[28:29], v[54:55], v[28:29], 0 op_sel_hi:[1,1,0]
	v_lshlrev_b32_e32 v32, 16, v8
	v_and_b32_e32 v33, 0xffff0000, v8
	v_add_f32_e32 v16, 1.0, v16
	v_pk_fma_f32 v[28:29], v[60:61], v[32:33], v[28:29]
	v_lshlrev_b32_e32 v32, 16, v4
	v_and_b32_e32 v33, 0xffff0000, v4
	v_rcp_f32_e32 v30, v16
	v_mul_f32_e32 v16, 0xbfb8aa3b, v27
	v_pk_fma_f32 v[28:29], v[64:65], v[32:33], v[28:29]
	v_lshlrev_b32_e32 v32, 16, v0
	v_and_b32_e32 v33, 0xffff0000, v0
	v_exp_f32_e32 v16, v16
	v_pk_fma_f32 v[28:29], v[90:91], v[32:33], v[28:29]
	v_pk_mul_f32 v[94:95], v[38:39], v[124:125] op_sel_hi:[0,1]
	v_mul_f32_e32 v0, 0xbfb8aa3b, v28
	v_exp_f32_e32 v0, v0
	v_lshlrev_b32_e32 v20, 16, v21
	v_and_b32_e32 v21, 0xffff0000, v21
	v_pk_mul_f32 v[126:127], v[38:39], v[126:127] op_sel_hi:[0,1]
	v_add_f32_e32 v16, 1.0, v16
	v_pk_fma_f32 v[20:21], v[94:95], v[20:21], v[24:25]
	v_pk_fma_f32 v[10:11], v[126:127], v[14:15], v[10:11]
	v_rcp_f32_e32 v31, v16
	v_mul_f32_e32 v16, 0xbfb8aa3b, v20
	v_mul_f32_e32 v14, 0xbfb8aa3b, v10
	v_mul_f32_e32 v15, 0xbfb8aa3b, v11
	v_exp_f32_e32 v16, v16
	v_add_f32_e32 v0, 1.0, v0
	v_exp_f32_e32 v14, v14
	v_exp_f32_e32 v15, v15
	v_rcp_f32_e32 v32, v0
	v_mul_f32_e32 v0, 0xbfb8aa3b, v29
	v_exp_f32_e32 v0, v0
	v_add_f32_e32 v16, 1.0, v16
	v_lshlrev_b32_e32 v12, 16, v13
	v_and_b32_e32 v13, 0xffff0000, v13
	v_add_f32_e32 v14, 1.0, v14
	v_add_f32_e32 v15, 1.0, v15
	v_rcp_f32_e32 v24, v16
	v_mul_f32_e32 v16, 0xbfb8aa3b, v21
	v_pk_fma_f32 v[12:13], v[34:35], v[12:13], 0 op_sel_hi:[1,1,0]
	v_lshlrev_b32_e32 v8, 16, v9
	v_and_b32_e32 v9, 0xffff0000, v9
	v_rcp_f32_e32 v14, v14
	v_rcp_f32_e32 v15, v15
	v_exp_f32_e32 v16, v16
	v_add_f32_e32 v0, 1.0, v0
	v_pk_fma_f32 v[8:9], v[36:37], v[8:9], v[12:13]
	v_lshlrev_b32_e32 v4, 16, v5
	v_and_b32_e32 v5, 0xffff0000, v5
	v_pk_mul_f32 v[76:77], v[38:39], v[120:121] op_sel_hi:[0,1]
	v_mul_f32_e32 v6, 0xbfb8aa3b, v3
	v_rcp_f32_e32 v33, v0
	v_pk_fma_f32 v[4:5], v[58:59], v[4:5], v[8:9]
	v_lshlrev_b32_e32 v0, 16, v1
	v_and_b32_e32 v1, 0xffff0000, v1
	v_exp_f32_e32 v6, v6
	v_pk_fma_f32 v[0:1], v[76:77], v[0:1], v[4:5]
	v_pk_mul_f32 v[10:11], v[10:11], v[14:15]
	v_mul_f32_e32 v4, 0xbfb8aa3b, v0
	v_mul_f32_e32 v5, 0xbfb8aa3b, v1
	v_add_f32_e32 v16, 1.0, v16
	v_exp_f32_e32 v4, v4
	v_exp_f32_e32 v5, v5
	v_pk_mul_f32 v[14:15], v[10:11], v[10:11]
	v_pk_mul_f32 v[18:19], v[18:19], v[22:23]
	v_rcp_f32_e32 v25, v16
	v_add_f32_e32 v6, 1.0, v6
	v_pk_mul_f32 v[22:23], v[18:19], v[18:19]
	v_add_f32_e32 v8, v14, v15
	v_rcp_f32_e32 v7, v6
	v_mul_f32_e32 v6, 0xbfb8aa3b, v2
	v_pk_mul_f32 v[26:27], v[26:27], v[30:31]
	v_add_f32_e32 v8, v22, v8
	v_exp_f32_e32 v6, v6
	v_pk_mul_f32 v[30:31], v[26:27], v[26:27]
	v_add_f32_e32 v4, 1.0, v4
	v_add_f32_e32 v5, 1.0, v5
	v_add_f32_e32 v8, v23, v8
	v_pk_mul_f32 v[20:21], v[20:21], v[24:25]
	v_rcp_f32_e32 v4, v4
	v_rcp_f32_e32 v5, v5
	v_add_f32_e32 v8, v30, v8
	v_pk_mul_f32 v[24:25], v[20:21], v[20:21]
	v_add_f32_e32 v8, v31, v8
	v_pk_mul_f32 v[28:29], v[28:29], v[32:33]
	v_add_f32_e32 v8, v24, v8
	v_add_f32_e32 v6, 1.0, v6
	v_pk_mul_f32 v[32:33], v[28:29], v[28:29]
	v_add_f32_e32 v8, v25, v8
	v_rcp_f32_e32 v6, v6
	v_pk_mul_f32 v[0:1], v[0:1], v[4:5]
	v_add_f32_e32 v8, v32, v8
	v_pk_mul_f32 v[4:5], v[0:1], v[0:1]
	v_add_f32_e32 v8, v33, v8
	v_pk_mul_f32 v[74:75], v[74:75], v[84:85]
	v_add_f32_e32 v4, v4, v8
	v_pk_mul_f32 v[84:85], v[74:75], v[74:75]
	v_add_f32_e32 v4, v5, v4
	v_pk_mul_f32 v[2:3], v[2:3], v[6:7]
	v_add_f32_e32 v4, v84, v4
	v_pk_mul_f32 v[6:7], v[2:3], v[2:3]
	v_add_f32_e32 v4, v85, v4
	v_add_f32_e32 v4, v6, v4
	v_add_f32_e32 v4, v7, v4
	ds_bpermute_b32 v5, v45, v4
	v_or_b32_e32 v34, 0x400, v39
	s_waitcnt lgkmcnt(0)
	v_add_f32_e32 v4, v4, v5
	ds_bpermute_b32 v5, v112, v4
	s_waitcnt lgkmcnt(0)
	v_add_f32_e32 v4, v4, v5
	ds_bpermute_b32 v5, v113, v4
	s_waitcnt lgkmcnt(0)
	v_add_f32_e32 v4, v4, v5
	v_add_f32_e32 v4, 0x358637bd, v4
	v_cmp_gt_f32_e32 vcc, s33, v4
	v_mul_f32_e32 v5, 0x4b800000, v4
	s_nop 0
	v_cndmask_b32_e32 v4, v4, v5, vcc
	v_rsq_f32_e32 v4, v4
	s_nop 0
	v_mul_f32_e32 v5, 0x45800000, v4
	v_cndmask_b32_e32 v16, v4, v5, vcc
	v_pk_mul_f32 v[4:5], v[10:11], v[16:17] op_sel_hi:[1,0]
	v_pk_mul_f32 v[6:7], v[18:19], v[16:17] op_sel_hi:[1,0]
	v_pk_mul_f32 v[8:9], v[26:27], v[16:17] op_sel_hi:[1,0]
	v_pk_mul_f32 v[10:11], v[20:21], v[16:17] op_sel_hi:[1,0]
	v_pk_mul_f32 v[12:13], v[28:29], v[16:17] op_sel_hi:[1,0]
	v_pk_mul_f32 v[14:15], v[0:1], v[16:17] op_sel_hi:[1,0]
	v_pk_mul_f32 v[0:1], v[74:75], v[16:17] op_sel_hi:[1,0]
	v_pk_mul_f32 v[2:3], v[2:3], v[16:17] op_sel_hi:[1,0]
	v_cvt_pk_bf16_f32 v16, v4, v5
	v_cvt_pk_bf16_f32 v18, v6, v7
	ds_write2_b32 v43, v16, v18 offset1:1
	v_cvt_pk_bf16_f32 v16, v8, v9
	v_cvt_pk_bf16_f32 v18, v10, v11
	ds_write2_b32 v43, v16, v18 offset0:2 offset1:3
	v_cvt_pk_bf16_f32 v16, v12, v13
	v_cvt_pk_bf16_f32 v18, v14, v15
	ds_write2_b32 v43, v16, v18 offset0:4 offset1:5
	v_cvt_pk_bf16_f32 v16, v0, v1
	v_cvt_pk_bf16_f32 v18, v2, v3
	ds_write2_b32 v43, v16, v18 offset0:6 offset1:7
	ds_write_b128 v110, v[4:7] offset:35328
	ds_write_b128 v110, v[8:11] offset:35344
	ds_write_b128 v110, v[12:15] offset:35360
	ds_write_b128 v110, v[0:3] offset:35376
	v_lshlrev_b32_e32 v16, 1, v34
	v_lshl_add_u64 v[0:1], v[46:47], 0, v[16:17]
	global_load_dwordx4 v[12:15], v[0:1], off
	global_load_dwordx4 v[30:33], v[0:1], off offset:16
	v_lshl_add_u64 v[0:1], v[48:49], 0, v[16:17]
	global_load_dwordx4 v[8:11], v[0:1], off
	global_load_dwordx4 v[26:29], v[0:1], off offset:16
	v_lshl_add_u64 v[0:1], v[50:51], 0, v[16:17]
	v_lshl_add_u64 v[18:19], v[52:53], 0, v[16:17]
	global_load_dwordx4 v[4:7], v[0:1], off
	global_load_dwordx4 v[22:25], v[0:1], off offset:16
	s_nop 0
	global_load_dwordx4 v[0:3], v[18:19], off
	s_nop 0
	global_load_dwordx4 v[18:21], v[18:19], off offset:16
	s_mov_b32 s8, 0
	s_ashr_i32 s9, s8, 31
	s_lshl_b64 s[8:9], s[8:9], 3
	s_add_u32 s8, s0, s8
	s_addc_u32 s9, s1, s9
	s_load_dwordx2 s[8:9], s[8:9], 0x90
	v_lshlrev_b32_e32 v16, 2, v34
	v_cmp_gt_u32_e32 vcc, 64, v106
	s_waitcnt lgkmcnt(0)
	s_add_u32 s98, s8, s16
	s_addc_u32 s99, s9, s17
	s_add_u32 s100, s8, s18
	s_addc_u32 s101, s9, s19
	s_add_u32 s30, s8, s22
	s_addc_u32 s31, s9, s23
	s_add_u32 s8, s8, s15
	s_addc_u32 s9, s9, s14
	global_load_dwordx4 v[52:55], v16, s[8:9] offset:48
	global_load_dwordx4 v[56:59], v16, s[8:9] offset:32
	global_load_dwordx4 v[48:51], v16, s[8:9] offset:16
	global_load_dwordx4 v[34:37], v16, s[8:9]
	global_load_dwordx4 v[140:143], v16, s[98:99] offset:48
	global_load_dwordx4 v[144:147], v16, s[98:99] offset:32
	global_load_dwordx4 v[148:151], v16, s[98:99] offset:16
	global_load_dwordx4 v[152:155], v16, s[98:99]
	global_load_dwordx4 v[156:159], v16, s[100:101] offset:48
	global_load_dwordx4 v[160:163], v16, s[100:101] offset:32
	global_load_dwordx4 v[164:167], v16, s[100:101] offset:16
	global_load_dwordx4 v[168:171], v16, s[100:101]
	global_load_dwordx4 v[172:175], v16, s[30:31] offset:48
	global_load_dwordx4 v[176:179], v16, s[30:31] offset:32
	global_load_dwordx4 v[180:183], v16, s[30:31] offset:16
	global_load_dwordx4 v[184:187], v16, s[30:31]
	s_mov_b32 s8, 0
	s_ashr_i32 s9, s8, 31
	s_lshl_b64 s[8:9], s[8:9], 3
	s_add_u32 s8, s0, s8
	s_addc_u32 s9, s1, s9
	s_load_dwordx2 s[8:9], s[8:9], 0x90
	s_waitcnt lgkmcnt(0)
	s_add_u32 s8, s8, s16
	s_addc_u32 s9, s9, s17
	s_waitcnt vmcnt(0)
	v_pk_mul_f32 v[70:71], v[44:45], v[52:53] op_sel_hi:[0,1]
	v_pk_mul_f32 v[56:57], v[44:45], v[56:57] op_sel_hi:[0,1]
	v_pk_mul_f32 v[48:49], v[44:45], v[48:49] op_sel_hi:[0,1]
	v_pk_mul_f32 v[34:35], v[44:45], v[34:35] op_sel_hi:[0,1]
	v_pk_mul_f32 v[36:37], v[44:45], v[36:37] op_sel_hi:[0,1]
	v_pk_mul_f32 v[50:51], v[44:45], v[50:51] op_sel_hi:[0,1]
	v_pk_mul_f32 v[62:63], v[44:45], v[58:59] op_sel_hi:[0,1]
	v_pk_mul_f32 v[78:79], v[44:45], v[54:55] op_sel_hi:[0,1]
	v_mov_b64_e32 v[66:67], v[140:141]
	v_mov_b64_e32 v[68:69], v[142:143]
	v_mov_b64_e32 v[72:73], v[144:145]
	v_mov_b64_e32 v[74:75], v[146:147]
	v_mov_b64_e32 v[58:59], v[148:149]
	v_mov_b64_e32 v[60:61], v[150:151]
	v_mov_b64_e32 v[44:45], v[152:153]
	v_mov_b64_e32 v[46:47], v[154:155]
	s_mov_b32 s8, 0
	s_ashr_i32 s9, s8, 31
	s_lshl_b64 s[8:9], s[8:9], 3
	s_add_u32 s8, s0, s8
	s_addc_u32 s9, s1, s9
	s_load_dwordx2 s[8:9], s[8:9], 0x90
	s_waitcnt lgkmcnt(0)
	s_add_u32 s8, s8, s18
	s_addc_u32 s9, s9, s19
	s_waitcnt vmcnt(3)
	v_pk_mul_f32 v[80:81], v[42:43], v[66:67] op_sel_hi:[0,1]
	s_waitcnt vmcnt(2)
	v_pk_mul_f32 v[64:65], v[42:43], v[72:73] op_sel_hi:[0,1]
	v_pk_mul_f32 v[72:73], v[42:43], v[74:75] op_sel_hi:[0,1]
	v_pk_mul_f32 v[86:87], v[42:43], v[68:69] op_sel_hi:[0,1]
	v_mov_b64_e32 v[88:89], v[156:157]
	v_mov_b64_e32 v[90:91], v[158:159]
	v_mov_b64_e32 v[74:75], v[160:161]
	v_mov_b64_e32 v[76:77], v[162:163]
	v_mov_b64_e32 v[66:67], v[164:165]
	v_mov_b64_e32 v[68:69], v[166:167]
	v_mov_b64_e32 v[82:83], v[168:169]
	v_mov_b64_e32 v[84:85], v[170:171]
	s_mov_b32 s8, 0
	s_ashr_i32 s9, s8, 31
	s_lshl_b64 s[8:9], s[8:9], 3
	s_add_u32 s8, s0, s8
	s_addc_u32 s9, s1, s9
	s_load_dwordx2 s[8:9], s[8:9], 0x90
	s_waitcnt vmcnt(4)
	v_pk_mul_f32 v[44:45], v[42:43], v[44:45] op_sel_hi:[0,1]
	v_pk_mul_f32 v[46:47], v[42:43], v[46:47] op_sel_hi:[0,1]
	v_pk_mul_f32 v[54:55], v[42:43], v[58:59] op_sel_hi:[0,1]
	v_pk_mul_f32 v[58:59], v[42:43], v[60:61] op_sel_hi:[0,1]
	s_waitcnt lgkmcnt(0)
	s_add_u32 s8, s8, s22
	s_addc_u32 s9, s9, s23
	v_mov_b64_e32 v[92:93], v[172:173]
	v_mov_b64_e32 v[94:95], v[174:175]
	v_mov_b64_e32 v[96:97], v[176:177]
	v_mov_b64_e32 v[98:99], v[178:179]
	v_mov_b64_e32 v[100:101], v[180:181]
	v_mov_b64_e32 v[102:103], v[182:183]
	v_mov_b64_e32 v[112:113], v[184:185]
	v_mov_b64_e32 v[114:115], v[186:187]
	s_waitcnt vmcnt(7)
	v_pk_mul_f32 v[88:89], v[40:41], v[88:89] op_sel_hi:[0,1]
	s_waitcnt vmcnt(6)
	v_pk_mul_f32 v[74:75], v[40:41], v[74:75] op_sel_hi:[0,1]
	s_waitcnt vmcnt(5)
	v_pk_mul_f32 v[60:61], v[40:41], v[66:67] op_sel_hi:[0,1]
	s_waitcnt vmcnt(4)
	v_pk_mul_f32 v[42:43], v[40:41], v[82:83] op_sel_hi:[0,1]
	v_pk_mul_f32 v[52:53], v[40:41], v[84:85] op_sel_hi:[0,1]
	v_pk_mul_f32 v[66:67], v[40:41], v[68:69] op_sel_hi:[0,1]
	v_pk_mul_f32 v[82:83], v[40:41], v[76:77] op_sel_hi:[0,1]
	v_pk_mul_f32 v[40:41], v[40:41], v[90:91] op_sel_hi:[0,1]
	s_waitcnt vmcnt(3)
	v_pk_mul_f32 v[92:93], v[38:39], v[92:93] op_sel_hi:[0,1]
	s_waitcnt vmcnt(2)
	v_pk_mul_f32 v[96:97], v[38:39], v[96:97] op_sel_hi:[0,1]
	s_waitcnt vmcnt(1)
	v_pk_mul_f32 v[84:85], v[38:39], v[100:101] op_sel_hi:[0,1]
	s_waitcnt vmcnt(0)
	v_pk_mul_f32 v[68:69], v[38:39], v[112:113] op_sel_hi:[0,1]
	v_pk_mul_f32 v[76:77], v[38:39], v[114:115] op_sel_hi:[0,1]
	v_pk_mul_f32 v[90:91], v[38:39], v[102:103] op_sel_hi:[0,1]
	v_pk_mul_f32 v[98:99], v[38:39], v[98:99] op_sel_hi:[0,1]
	v_pk_mul_f32 v[38:39], v[38:39], v[94:95] op_sel_hi:[0,1]
	v_lshlrev_b32_e32 v94, 16, v33
	v_and_b32_e32 v95, 0xffff0000, v33
	v_pk_fma_f32 v[78:79], v[78:79], v[94:95], 0 op_sel_hi:[1,1,0]
	v_lshlrev_b32_e32 v94, 16, v29
	v_and_b32_e32 v95, 0xffff0000, v29
	v_pk_fma_f32 v[78:79], v[86:87], v[94:95], v[78:79]
	v_lshlrev_b32_e32 v86, 16, v25
	v_and_b32_e32 v87, 0xffff0000, v25
	v_pk_fma_f32 v[40:41], v[40:41], v[86:87], v[78:79]
	v_lshlrev_b32_e32 v78, 16, v21
	v_and_b32_e32 v79, 0xffff0000, v21
	v_pk_fma_f32 v[38:39], v[38:39], v[78:79], v[40:41]
	v_lshlrev_b32_e32 v78, 16, v32
	v_and_b32_e32 v79, 0xffff0000, v32
	v_pk_fma_f32 v[32:33], v[70:71], v[78:79], 0 op_sel_hi:[1,1,0]
	v_lshlrev_b32_e32 v70, 16, v28
	v_and_b32_e32 v71, 0xffff0000, v28
	v_pk_fma_f32 v[28:29], v[80:81], v[70:71], v[32:33]
	v_lshlrev_b32_e32 v32, 16, v24
	v_and_b32_e32 v33, 0xffff0000, v24
	v_pk_fma_f32 v[24:25], v[88:89], v[32:33], v[28:29]
	v_lshlrev_b32_e32 v28, 16, v20
	v_and_b32_e32 v29, 0xffff0000, v20
	v_pk_fma_f32 v[20:21], v[92:93], v[28:29], v[24:25]
	v_lshlrev_b32_e32 v28, 16, v31
	v_and_b32_e32 v29, 0xffff0000, v31
	v_pk_fma_f32 v[28:29], v[62:63], v[28:29], 0 op_sel_hi:[1,1,0]
	v_lshlrev_b32_e32 v62, 16, v30
	v_and_b32_e32 v63, 0xffff0000, v30
	v_pk_fma_f32 v[30:31], v[56:57], v[62:63], 0 op_sel_hi:[1,1,0]
	v_lshlrev_b32_e32 v56, 16, v26
	v_and_b32_e32 v57, 0xffff0000, v26
	v_lshlrev_b32_e32 v32, 16, v27
	v_and_b32_e32 v33, 0xffff0000, v27
	v_pk_fma_f32 v[26:27], v[64:65], v[56:57], v[30:31]
	v_lshlrev_b32_e32 v30, 16, v22
	v_and_b32_e32 v31, 0xffff0000, v22
	v_pk_fma_f32 v[28:29], v[72:73], v[32:33], v[28:29]
	v_lshlrev_b32_e32 v32, 16, v23
	v_and_b32_e32 v33, 0xffff0000, v23
	v_pk_fma_f32 v[22:23], v[74:75], v[30:31], v[26:27]
	v_lshlrev_b32_e32 v26, 16, v18
	v_and_b32_e32 v27, 0xffff0000, v18
	v_pk_fma_f32 v[28:29], v[82:83], v[32:33], v[28:29]
	v_lshlrev_b32_e32 v32, 16, v19
	v_and_b32_e32 v33, 0xffff0000, v19
	v_pk_fma_f32 v[18:19], v[96:97], v[26:27], v[22:23]
	v_lshlrev_b32_e32 v26, 16, v15
	v_and_b32_e32 v27, 0xffff0000, v15
	v_pk_fma_f32 v[26:27], v[50:51], v[26:27], 0 op_sel_hi:[1,1,0]
	v_lshlrev_b32_e32 v50, 16, v14
	v_and_b32_e32 v51, 0xffff0000, v14
	v_mul_f32_e32 v16, 0xbfb8aa3b, v39
	v_lshlrev_b32_e32 v30, 16, v11
	v_and_b32_e32 v31, 0xffff0000, v11
	v_pk_fma_f32 v[14:15], v[48:49], v[50:51], 0 op_sel_hi:[1,1,0]
	v_lshlrev_b32_e32 v48, 16, v10
	v_and_b32_e32 v49, 0xffff0000, v10
	v_exp_f32_e32 v16, v16
	v_pk_fma_f32 v[26:27], v[58:59], v[30:31], v[26:27]
	v_lshlrev_b32_e32 v30, 16, v7
	v_and_b32_e32 v31, 0xffff0000, v7
	v_pk_fma_f32 v[10:11], v[54:55], v[48:49], v[14:15]
	v_lshlrev_b32_e32 v14, 16, v6
	v_and_b32_e32 v15, 0xffff0000, v6
	v_pk_fma_f32 v[26:27], v[66:67], v[30:31], v[26:27]
	v_lshlrev_b32_e32 v30, 16, v3
	v_and_b32_e32 v31, 0xffff0000, v3
	v_pk_fma_f32 v[6:7], v[60:61], v[14:15], v[10:11]
	v_lshlrev_b32_e32 v10, 16, v2
	v_and_b32_e32 v11, 0xffff0000, v2
	v_pk_fma_f32 v[26:27], v[90:91], v[30:31], v[26:27]
	v_pk_fma_f32 v[6:7], v[84:85], v[10:11], v[6:7]
	v_mul_f32_e32 v3, 0xbfb8aa3b, v27
	v_mul_f32_e32 v2, 0xbfb8aa3b, v7
	v_add_f32_e32 v16, 1.0, v16
	v_exp_f32_e32 v3, v3
	v_exp_f32_e32 v2, v2
	v_rcp_f32_e32 v41, v16
	v_mul_f32_e32 v16, 0xbfb8aa3b, v38
	v_exp_f32_e32 v16, v16
	v_add_f32_e32 v3, 1.0, v3
	v_add_f32_e32 v2, 1.0, v2
	v_rcp_f32_e32 v31, v3
	v_mul_f32_e32 v3, 0xbfb8aa3b, v26
	v_rcp_f32_e32 v11, v2
	v_mul_f32_e32 v2, 0xbfb8aa3b, v6
	v_add_f32_e32 v16, 1.0, v16
	v_exp_f32_e32 v3, v3
	v_exp_f32_e32 v2, v2
	v_rcp_f32_e32 v40, v16
	v_mul_f32_e32 v16, 0xbfb8aa3b, v21
	v_exp_f32_e32 v16, v16
	v_add_f32_e32 v3, 1.0, v3
	v_add_f32_e32 v2, 1.0, v2
	v_rcp_f32_e32 v30, v3
	v_rcp_f32_e32 v10, v2
	v_lshlrev_b32_e32 v2, 16, v13
	v_and_b32_e32 v3, 0xffff0000, v13
	v_add_f32_e32 v16, 1.0, v16
	v_pk_fma_f32 v[2:3], v[36:37], v[2:3], 0 op_sel_hi:[1,1,0]
	v_lshlrev_b32_e32 v14, 16, v9
	v_and_b32_e32 v15, 0xffff0000, v9
	v_rcp_f32_e32 v25, v16
	v_mul_f32_e32 v16, 0xbfb8aa3b, v20
	v_pk_fma_f32 v[2:3], v[46:47], v[14:15], v[2:3]
	v_lshlrev_b32_e32 v14, 16, v5
	v_and_b32_e32 v15, 0xffff0000, v5
	v_exp_f32_e32 v16, v16
	v_pk_fma_f32 v[2:3], v[52:53], v[14:15], v[2:3]
	v_lshlrev_b32_e32 v14, 16, v1
	v_and_b32_e32 v15, 0xffff0000, v1
	v_pk_fma_f32 v[2:3], v[76:77], v[14:15], v[2:3]
	v_add_f32_e32 v16, 1.0, v16
	v_mul_f32_e32 v1, 0xbfb8aa3b, v3
	v_exp_f32_e32 v1, v1
	v_pk_fma_f32 v[28:29], v[98:99], v[32:33], v[28:29]
	v_rcp_f32_e32 v24, v16
	v_mul_f32_e32 v16, 0xbfb8aa3b, v29
	v_exp_f32_e32 v16, v16
	v_add_f32_e32 v1, 1.0, v1
	v_rcp_f32_e32 v15, v1
	v_mul_f32_e32 v1, 0xbfb8aa3b, v2
	v_exp_f32_e32 v1, v1
	v_add_f32_e32 v16, 1.0, v16
	v_lshlrev_b32_e32 v36, 16, v12
	v_and_b32_e32 v37, 0xffff0000, v12
	v_rcp_f32_e32 v33, v16
	v_mul_f32_e32 v16, 0xbfb8aa3b, v28
	v_pk_fma_f32 v[12:13], v[34:35], v[36:37], 0 op_sel_hi:[1,1,0]
	v_lshlrev_b32_e32 v34, 16, v8
	v_and_b32_e32 v35, 0xffff0000, v8
	v_exp_f32_e32 v16, v16
	v_pk_fma_f32 v[8:9], v[44:45], v[34:35], v[12:13]
	v_lshlrev_b32_e32 v12, 16, v4
	v_and_b32_e32 v13, 0xffff0000, v4
	v_add_f32_e32 v1, 1.0, v1
	v_pk_fma_f32 v[4:5], v[42:43], v[12:13], v[8:9]
	v_lshlrev_b32_e32 v8, 16, v0
	v_and_b32_e32 v9, 0xffff0000, v0
	v_rcp_f32_e32 v14, v1
	v_pk_fma_f32 v[0:1], v[68:69], v[8:9], v[4:5]
	v_add_f32_e32 v16, 1.0, v16
	v_mul_f32_e32 v4, 0xbfb8aa3b, v1
	v_exp_f32_e32 v4, v4
	v_rcp_f32_e32 v32, v16
	v_mul_f32_e32 v16, 0xbfb8aa3b, v19
	v_exp_f32_e32 v16, v16
	v_add_f32_e32 v4, 1.0, v4
	v_rcp_f32_e32 v5, v4
	v_mul_f32_e32 v4, 0xbfb8aa3b, v0
	v_add_f32_e32 v16, 1.0, v16
	v_exp_f32_e32 v4, v4
	v_rcp_f32_e32 v23, v16
	v_mul_f32_e32 v16, 0xbfb8aa3b, v18
	v_exp_f32_e32 v16, v16
	v_add_f32_e32 v4, 1.0, v4
	v_rcp_f32_e32 v4, v4
	v_pk_mul_f32 v[2:3], v[2:3], v[14:15]
	v_add_f32_e32 v16, 1.0, v16
	v_rcp_f32_e32 v22, v16
	v_pk_mul_f32 v[0:1], v[0:1], v[4:5]
	ds_write_b128 v110, v[0:3] offset:34816
	v_pk_mul_f32 v[0:1], v[6:7], v[10:11]
	v_pk_mul_f32 v[2:3], v[26:27], v[30:31]
	ds_write_b128 v110, v[0:3] offset:34832
	v_pk_mul_f32 v[0:1], v[18:19], v[22:23]
	v_pk_mul_f32 v[2:3], v[28:29], v[32:33]
	ds_write_b128 v110, v[0:3] offset:34848
	v_pk_mul_f32 v[0:1], v[20:21], v[24:25]
	v_pk_mul_f32 v[2:3], v[38:39], v[40:41]
	v_lshl_add_u32 v44, v106, 2, 0
	ds_write_b128 v110, v[0:3] offset:34864
	s_and_saveexec_b64 s[8:9], vcc
	s_cbranch_execz .LBB0_763
	v_or_b32_e32 v0, s5, v106
	v_ashrrev_i32_e32 v1, 31, v0
	v_lshlrev_b64 v[0:1], 5, v[0:1]
	v_lshl_add_u64 v[0:1], s[42:43], 0, v[0:1]
	s_lshl_b32 s52, s37, 2
	v_lshl_add_u64 v[0:1], v[0:1], 0, s[52:53]
	v_mov_b32_e32 v2, v189
	s_nop 0
	v_mov_b32_e32 v0, v190
	s_mov_b32 s38, 0
	s_ashr_i32 s39, s38, 31
	s_lshl_b64 s[38:39], s[38:39], 3
	s_add_u32 s38, s0, s38
	s_addc_u32 s39, s1, s39
	s_or_b32 s48, s37, s35
	s_ashr_i32 s49, s48, 31
	s_lshl_b64 s[48:49], s[48:49], 2
	s_mov_b32 s2, 0xbfb8aa3b
	s_waitcnt lgkmcnt(0)
	s_add_u32 s38, s38, s48
	s_addc_u32 s39, s39, s49
	v_mov_b32_e32 v1, v191
	s_mov_b32 s38, 0
	s_ashr_i32 s39, s38, 31
	s_lshl_b64 s[38:39], s[38:39], 3
	s_add_u32 s38, s0, s38
	s_addc_u32 s39, s1, s39
	s_waitcnt lgkmcnt(0)
	s_add_u32 s38, s38, s48
	s_addc_u32 s39, s39, s49
	v_mov_b32_e32 v3, v192
	s_waitcnt vmcnt(0)
	v_mul_f32_e32 v0, 0xbfb8aa3b, v0
	v_exp_f32_e32 v0, v0
	v_mul_f32_e32 v1, 0x3fb8aa3b, v1
	v_exp_f32_e32 v1, v1
	v_add_f32_e32 v0, 1.0, v0
	v_rcp_f32_e32 v0, v0
	v_add_f32_e32 v2, v2, v3
	v_max_f32_e32 v4, 0, v2
	v_mul_f32_e64 v2, |v2|, s2
	v_exp_f32_e32 v5, v2
	s_mov_b32 s2, 0x3f2aaaab
	v_add_f32_e32 v6, 1.0, v5
	v_add_f32_e32 v2, -1.0, v6
	v_sub_f32_e32 v3, v2, v6
	v_add_f32_e32 v3, 1.0, v3
	v_sub_f32_e32 v2, v5, v2
	v_add_f32_e32 v7, v2, v3
	v_frexp_mant_f32_e32 v2, v6
	v_cmp_gt_f32_e32 vcc, s2, v2
	v_cvt_f64_f32_e32 v[2:3], v6
	v_frexp_exp_i32_f64_e32 v2, v[2:3]
	v_subbrev_co_u32_e32 v2, vcc, 0, v2, vcc
	v_sub_u32_e32 v3, 0, v2
	v_ldexp_f32 v6, v6, v3
	v_ldexp_f32 v3, v7, v3
	v_add_f32_e32 v7, -1.0, v6
	v_add_f32_e32 v8, 1.0, v7
	v_sub_f32_e32 v8, v6, v8
	v_add_f32_e32 v8, v3, v8
	v_add_f32_e32 v9, v7, v8
	v_sub_f32_e32 v7, v9, v7
	v_sub_f32_e32 v7, v8, v7
	v_add_f32_e32 v8, 1.0, v6
	v_add_f32_e32 v10, -1.0, v8
	v_sub_f32_e32 v6, v6, v10
	v_add_f32_e32 v3, v3, v6
	v_add_f32_e32 v6, v8, v3
	v_sub_f32_e32 v8, v6, v8
	v_sub_f32_e32 v3, v3, v8
	v_rcp_f32_e32 v8, v6
	v_cvt_f32_i32_e32 v2, v2
	s_mov_b32 s2, 0x3f317218
	v_mul_f32_e32 v10, v9, v8
	v_mul_f32_e32 v11, v6, v10
	v_fma_f32 v12, v10, v6, -v11
	v_fmac_f32_e32 v12, v10, v3
	v_add_f32_e32 v13, v11, v12
	v_sub_f32_e32 v14, v9, v13
	v_sub_f32_e32 v9, v9, v14
	v_sub_f32_e32 v11, v13, v11
	v_sub_f32_e32 v9, v9, v13
	v_add_f32_e32 v7, v7, v9
	v_sub_f32_e32 v9, v11, v12
	v_add_f32_e32 v7, v9, v7
	v_add_f32_e32 v9, v14, v7
	v_mul_f32_e32 v11, v8, v9
	v_mul_f32_e32 v12, v6, v11
	v_fma_f32 v6, v11, v6, -v12
	v_fmac_f32_e32 v6, v11, v3
	v_sub_f32_e32 v3, v14, v9
	v_add_f32_e32 v3, v7, v3
	v_add_f32_e32 v7, v12, v6
	v_sub_f32_e32 v13, v9, v7
	v_sub_f32_e32 v9, v9, v13
	v_sub_f32_e32 v12, v7, v12
	v_sub_f32_e32 v7, v9, v7
	v_add_f32_e32 v3, v3, v7
	v_sub_f32_e32 v6, v12, v6
	v_add_f32_e32 v3, v6, v3
	v_add_f32_e32 v6, v10, v11
	v_add_f32_e32 v3, v13, v3
	v_sub_f32_e32 v7, v6, v10
	v_mul_f32_e32 v3, v8, v3
	v_sub_f32_e32 v7, v11, v7
	v_add_f32_e32 v3, v7, v3
	v_mul_f32_e32 v10, 0x3f317218, v2
	v_add_f32_e32 v7, v6, v3
	v_fma_f32 v11, v2, s2, -v10
	v_mul_f32_e32 v8, v7, v7
	v_fmac_f32_e32 v11, 0xb102e308, v2
	v_sub_f32_e32 v2, v7, v6
	v_fmamk_f32 v9, v8, 0x3e9b6dac, v232
	v_sub_f32_e32 v2, v3, v2
	v_add_f32_e32 v3, v10, v11
	v_fmaak_f32 v9, v8, v9, 0x3f2aaada
	v_sub_f32_e32 v6, v3, v10
	v_ldexp_f32 v10, v7, 1
	v_mul_f32_e32 v7, v7, v8
	v_mul_f32_e32 v7, v7, v9
	v_add_f32_e32 v8, v10, v7
	v_sub_f32_e32 v9, v8, v10
	v_ldexp_f32 v2, v2, 1
	v_sub_f32_e32 v7, v7, v9
	v_add_f32_e32 v2, v2, v7
	v_add_f32_e32 v7, v8, v2
	v_sub_f32_e32 v8, v7, v8
	v_sub_f32_e32 v2, v2, v8
	v_add_f32_e32 v8, v3, v7
	v_sub_f32_e32 v9, v8, v3
	v_sub_f32_e32 v10, v8, v9
	v_sub_f32_e32 v6, v11, v6
	v_sub_f32_e32 v3, v3, v10
	v_sub_f32_e32 v7, v7, v9
	v_add_f32_e32 v3, v7, v3
	v_add_f32_e32 v7, v6, v2
	v_sub_f32_e32 v9, v7, v6
	v_sub_f32_e32 v10, v7, v9
	v_sub_f32_e32 v6, v6, v10
	v_sub_f32_e32 v2, v2, v9
	v_add_f32_e32 v3, v7, v3
	v_add_f32_e32 v2, v2, v6
	v_add_f32_e32 v6, v8, v3
	v_sub_f32_e32 v7, v6, v8
	v_sub_f32_e32 v3, v3, v7
	v_add_f32_e32 v2, v2, v3
	s_mov_b32 s2, 0x7f800000
	v_add_f32_e32 v2, v6, v2
	v_cmp_neq_f32_e32 vcc, s2, v5
	s_mov_b32 s2, 0x33800000
	s_nop 0
	v_cndmask_b32_e32 v2, v236, v2, vcc
	v_cmp_ngt_f32_e32 vcc, -1.0, v5
	s_nop 1
	v_cndmask_b32_e32 v2, v237, v2, vcc
	v_cmp_neq_f32_e32 vcc, -1.0, v5
	s_nop 1
	v_cndmask_b32_e32 v2, v238, v2, vcc
	v_cmp_lt_f32_e64 vcc, |v5|, s2
	s_nop 1
	v_cndmask_b32_e32 v2, v2, v5, vcc
	v_add_f32_e32 v2, v4, v2
	v_add_u32_e32 v4, -1, v234
	v_cmp_lt_i32_e32 vcc, v4, v111
	v_mul_f32_e64 v3, v2, -v1
	s_nop 0
	v_cndmask_b32_e32 v4, v4, v234, vcc
	v_lshlrev_b32_e32 v4, 2, v4
	ds_bpermute_b32 v4, v4, v3
	v_cmp_eq_u32_e32 vcc, 0, v106
	s_waitcnt lgkmcnt(0)
	v_fma_f32 v1, v2, -v1, v4
	v_add_u32_e32 v2, -2, v234
	v_cndmask_b32_e32 v1, v1, v3, vcc
	v_cmp_lt_i32_e32 vcc, v2, v111
	v_add_u32_e32 v3, 0x1cc00, v44
	s_nop 0
	v_cndmask_b32_e32 v2, v2, v234, vcc
	v_lshlrev_b32_e32 v2, 2, v2
	ds_bpermute_b32 v2, v2, v1
	v_cmp_gt_u32_e32 vcc, 2, v106
	s_waitcnt lgkmcnt(0)
	v_add_f32_e32 v2, v1, v2
	v_cndmask_b32_e32 v1, v2, v1, vcc
	v_add_u32_e32 v2, -4, v234
	v_cmp_lt_i32_e32 vcc, v2, v111
	s_nop 1
	v_cndmask_b32_e32 v2, v2, v234, vcc
	v_lshlrev_b32_e32 v2, 2, v2
	ds_bpermute_b32 v2, v2, v1
	v_cmp_gt_u32_e32 vcc, 4, v106
	s_waitcnt lgkmcnt(0)
	v_add_f32_e32 v2, v1, v2
	v_cndmask_b32_e32 v1, v2, v1, vcc
	v_add_u32_e32 v2, -8, v234
	v_cmp_lt_i32_e32 vcc, v2, v111
	s_nop 1
	v_cndmask_b32_e32 v2, v2, v234, vcc
	v_lshlrev_b32_e32 v2, 2, v2
	ds_bpermute_b32 v2, v2, v1
	v_cmp_gt_u32_e32 vcc, 8, v106
	s_waitcnt lgkmcnt(0)
	v_add_f32_e32 v2, v1, v2
	v_cndmask_b32_e32 v1, v2, v1, vcc
	v_add_u32_e32 v2, -16, v234
	v_cmp_lt_i32_e32 vcc, v2, v111
	s_nop 1
	v_cndmask_b32_e32 v2, v2, v234, vcc
	v_lshlrev_b32_e32 v2, 2, v2
	ds_bpermute_b32 v2, v2, v1
	v_cmp_gt_u32_e32 vcc, 16, v106
	s_waitcnt lgkmcnt(0)
	v_add_f32_e32 v2, v1, v2
	v_cndmask_b32_e32 v2, v2, v1, vcc
	v_subrev_u32_e32 v1, 32, v234
	v_cmp_lt_i32_e32 vcc, v1, v111
	s_nop 1
	v_cndmask_b32_e32 v1, v1, v234, vcc
	v_lshlrev_b32_e32 v1, 2, v1
	ds_bpermute_b32 v1, v1, v2
	v_cmp_gt_u32_e32 vcc, 32, v106
	s_waitcnt lgkmcnt(0)
	v_add_f32_e32 v1, v2, v1
	v_cndmask_b32_e32 v2, v1, v2, vcc
	ds_write_b32 v3, v2
	v_add_u32_e32 v2, 0x1cd00, v44
	v_cmp_eq_u32_e32 vcc, 63, v106
	ds_write_b32 v2, v0
	s_and_b64 exec, exec, vcc
	s_cbranch_execz .LBB0_763
	v_mul_f32_e32 v0, 0x3fb8aa3b, v1
	v_exp_f32_e32 v2, v0
	v_mov_b64_e32 v[0:1], s[92:93]
	global_store_dword v[0:1], v2, off
